# NA and SWA attention unit prologues: K(1) tile load (and the NA bias-table load) issued with the first load batch, one wait instead of two/three serial round trips
# baseline (speedup 1.0000x reference)
; #define LOADK(t) do { const int kp_ = TILE_KPOS(t); kreg = *(const u32x4*)((const char*)P.K + (size_t)(koff + (unsigned)(kp_ * KPITCH * 2))); if (VAR == 0 && tid < 256) pereg = *(const u32x4*)((const char*)P.KPE + (size_t)(peoff + (unsigned)(kp_ * 64))); } while (0)
; #define LOADV(t) do { const int kp_ = TILE_KPOS(t); vreg = *(const u32x4*)((const char*)P.VT + (size_t)(voff + (unsigned)(kp_ * 2))); } while (0)
; #define STOREK(buf) do { LAS unsigned char* kb_ = lds + (buf) * ABUF; *(LAS u32x4*)(kb_ + (tid >> 3) * KP + (tid & 7) * 16) = kreg; \
;         if (VAR == 0 && tid < 256) *(LAS u32x4*)(kb_ + (tid >> 2) * KP + 128 + (tid & 3) * 16) = pereg; } while (0)
; #define STOREV(buf) do { *(LAS u32x4*)(lds + (buf) * ABUF + KT_BYTES + (tid >> 3) * VP + (tid & 7) * 16) = vreg; } while (0)
; template <int VAR>
; __device__ __forceinline__ void attn_phase(LAS unsigned char* lds, const AttnP P, int vcu, int G, int wave_s) {
;     ...
;         if (VAR == 2 && !isctx) { if (tid < 465) bias_lds[tid] = P.bias[hq * 465 + tid] * LOG2E; }
;         bf16x8 qf[ND0];
;         { const bf16_t* qp = P.Q + (size_t)(qrow + r32) * QPITCH + hq * QH + hi * 8;
; #pragma unroll
;           for (int d0 = 0; d0 < ND0; ++d0) qf[d0] = *(const bf16x8*)(qp + d0 * 16); }
;         f32x16 o0 = {}, o1 = {};
;         const unsigned koff = (unsigned)(((b * KVLEN + (tid >> 3)) * KPITCH + hk * 64 + (tid & 7) * 8) * 2);
;         const unsigned peoff = (unsigned)(((b * KVLEN + (tid >> 2)) * 32 + (tid & 3) * 8) * 2);
;         const unsigned voff = (unsigned)(((b * VCOLS + hk * 64 + (tid >> 3)) * KVLEN + (tid & 7) * 8) * 2);
;     ...
;         LOADK(0); LOADV(0); STOREK(0); STOREV(0);
;         if (nt > 1) { LOADK(1); STOREK(1); }
;         __syncthreads();
.LBB0_1025:
	s_mul_i32 s0, s10, 0x1d1
	v_add_u32_e32 v2, s0, v137
	v_readlane_b32 s36, v252, 41
	v_ashrrev_i32_e32 v3, 31, v2
	v_readlane_b32 s46, v252, 51
	v_readlane_b32 s47, v252, 52
	v_readlane_b32 s37, v252, 42
	v_readlane_b32 s38, v252, 43
	v_lshl_add_u64 v[2:3], v[2:3], 2, s[46:47]
	global_load_dword v149, v[2:3], off
	v_readlane_b32 s39, v252, 44
	v_readlane_b32 s40, v252, 45
	v_readlane_b32 s41, v252, 46
	v_readlane_b32 s42, v252, 47
	v_readlane_b32 s43, v252, 48
	v_readlane_b32 s44, v252, 49
	v_readlane_b32 s45, v252, 50
	v_readlane_b32 s48, v252, 53
	v_readlane_b32 s49, v252, 54
	v_readlane_b32 s50, v252, 55
	v_readlane_b32 s51, v252, 56
.LBB0_1026:
	s_or_b64 exec, exec, s[6:7]
	v_add_u32_e32 v2, s21, v139
	v_ashrrev_i32_e32 v3, 31, v2
	v_lshlrev_b64 v[2:3], 11, v[2:3]
	v_readlane_b32 s36, v255, 18
	v_lshl_add_u64 v[2:3], s[72:73], 0, v[2:3]
	s_lshl_b32 s0, s10, 7
	s_mov_b32 s1, s36
	v_lshl_add_u64 v[2:3], v[2:3], 0, s[0:1]
	s_mul_i32 s0, s9, 0x2100
	s_lshl_b32 s22, s10, 6
	v_add_lshl_u32 v1, s0, v143, 10
	s_lshl_b32 s0, s9, 10
	v_lshlrev_b32_e32 v4, 1, v136
	v_mov_b32_e32 v5, v0
	v_or3_b32 v1, v1, s22, v138
	s_or_b32 s0, s0, s22
	v_lshl_add_u64 v[2:3], v[2:3], 0, v[4:5]
	v_lshlrev_b32_e32 v141, 1, v1
	v_add_u32_e32 v1, s0, v143
	s_movk_i32 s0, 0x2100
	global_load_dwordx4 v[112:115], v[2:3], off
	global_load_dwordx4 v[116:119], v[2:3], off offset:32
	global_load_dwordx4 v[120:123], v[2:3], off offset:64
	global_load_dwordx4 v[124:127], v[2:3], off offset:96
	v_mul_lo_u32 v1, v1, s0
	v_or_b32_e32 v1, v1, v138
	v_lshlrev_b32_e32 v185, 1, v1
	global_load_dwordx4 v[128:131], v141, s[52:53]
	global_load_dwordx4 v[132:135], v185, s[56:57]
	v_add_u32_e32 v1, 0x20000, v141
	global_load_dwordx4 v[150:153], v1, s[52:53]
	s_cmp_lt_i32 s23, 2
	v_readlane_b32 s37, v255, 19
	v_readlane_b32 s38, v255, 20
	v_readlane_b32 s39, v255, 21
	v_readlane_b32 s40, v255, 22
	v_readlane_b32 s41, v255, 23
	v_readlane_b32 s42, v255, 24
	v_readlane_b32 s43, v255, 25
	v_readlane_b32 s44, v255, 26
	v_readlane_b32 s45, v255, 27
	v_readlane_b32 s46, v255, 28
	v_readlane_b32 s47, v255, 29
	v_readlane_b32 s48, v255, 30
	v_readlane_b32 s49, v255, 31
	v_readlane_b32 s50, v255, 32
	v_readlane_b32 s51, v255, 33
	s_waitcnt vmcnt(0)
	s_cmp_eq_u32 s23, 4
	s_cbranch_scc1 .Lna_nobias
	s_and_saveexec_b64 s[6:7], s[4:5]
	v_mul_f32_e32 v149, 0x3fb8aa3b, v149
	ds_write_b32 v142, v149 offset:45056
	s_or_b64 exec, exec, s[6:7]
.Lna_nobias:
	ds_write_b128 v144, v[128:131]
	ds_write_b128 v182, v[132:135] offset:13312
	s_cmp_lt_i32 s23, 2
	s_cbranch_scc1 .LBB0_1028
	ds_write_b128 v144, v[150:153] offset:22528

; template <int VAR>
; __device__ __forceinline__ void attn_phase(LAS unsigned char* lds, const AttnP P, int vcu, int G, int wave_s) {
;     ...
;             if (!isctx) { const int blk = u & 63, hp = (u >> 6) & 7; b = u >> 9; hq = 2 * hp + (w >> 2); hk = hp >> 1; qrow = b * SEQ + blk * 128 + 32 * (w & 3);
;                           const int jlo = blk == 0 ? 2 : 0, jhi = blk == 63 ? 4 : 6; nt = 4 + jhi - jlo; p_a = blk * 128 - 128 + 64 * jlo; p_b = blk * 128 + 32 * (w & 3); }
;             else { const int cu = u - 4096, half = cu & 1, hp = (cu >> 1) & 7; b = cu >> 4; hq = 2 * hp + (w >> 2); hk = hp >> 1; qrow = ML + b * 256 + half * 128 + 32 * (w & 3); nt = 4; }
;         } else {
;             if (!isctx) { const int rq = u & 31; hq = (u >> 5) & 15; b = u >> 9; const int r0 = 4 * rq; qrow = b * SEQ + (r0 + (w >> 1)) * 64 + 32 * (w & 1);
;                           int lo = r0 - 4; lo = lo < 0 ? 0 : (lo > 120 ? 120 : lo); int h2 = r0 - 1; h2 = h2 < 0 ? 0 : (h2 > 120 ? 120 : h2); nt = 4 + (h2 + 8 - lo); p_a = lo; p_b = r0 + (w >> 1); }
;             else { const int cu = u - 4096; b = cu >> 4; hq = cu & 15; qrow = ML + b * 256 + 32 * w; nt = 4; }
;             hk = hq;
;         }
;         if (VAR == 2 && !isctx) { if (tid < 465) bias_lds[tid] = P.bias[hq * 465 + tid] * LOG2E; }
;         bf16x8 qf[ND0];
;         { const bf16_t* qp = P.Q + (size_t)(qrow + r32) * QPITCH + hq * QH + hi * 8;
; #pragma unroll
;           for (int d0 = 0; d0 < ND0; ++d0) qf[d0] = *(const bf16x8*)(qp + d0 * 16); }
;         f32x16 o0 = {}, o1 = {};
;         const unsigned koff = (unsigned)(((b * KVLEN + (tid >> 3)) * KPITCH + hk * 64 + (tid & 7) * 8) * 2);
;         const unsigned peoff = (unsigned)(((b * KVLEN + (tid >> 2)) * 32 + (tid & 3) * 8) * 2);
;         const unsigned voff = (unsigned)(((b * VCOLS + hk * 64 + (tid >> 3)) * KVLEN + (tid & 7) * 8) * 2);
;         u32x4 kreg, pereg = {}, vreg;
;     ...
;         const int rot = (VAR == 0 && !isctx) ? ((vcu & 31) * 4 + (vcu >> 5)) % 132 : 0;
;         int na_rs = 0; if (VAR == 2) { na_rs = p_b - 4; na_rs = na_rs < 0 ? 0 : (na_rs > 120 ? 120 : na_rs); }
;         LOADK(0); LOADV(0); STOREK(0); STOREV(0);
;         if (nt > 1) { LOADK(1); STOREK(1); }
;         __syncthreads();
;         f32x16 pc0, pc1; const f32x16 zero16 = {};
;         QK_TILE(pc0, pc1, 0, zero16);
;         float mref = rowmax32(pc0, pc1), lrun = 0.f;
.LBB0_1124:
	s_and_b32 s0, s5, 7
	s_or_b32 s22, s9, s20
	s_lshl_b32 s0, s0, 1
	v_add_u32_e32 v2, s22, v215
	s_add_i32 s4, s0, s19
	v_ashrrev_i32_e32 v3, 31, v2
	v_lshlrev_b64 v[2:3], 11, v[2:3]
	s_lshl_b32 s0, s4, 6
	s_mulk_i32 s7, 0x2100
	s_lshl_b32 s5, s5, 5
	v_lshl_add_u64 v[2:3], s[72:73], 0, v[2:3]
	s_ashr_i32 s1, s0, 31
	v_add_lshl_u32 v1, s7, v220, 8
	s_and_b32 s5, s5, 0xc0
	v_lshl_add_u64 v[2:3], s[0:1], 1, v[2:3]
	v_mov_b32_e32 v217, v0
	v_or3_b32 v1, v1, s5, v214
	s_add_i32 s5, s5, s8
	v_lshl_add_u64 v[2:3], v[2:3], 0, v[216:217]
	v_lshlrev_b32_e32 v217, 1, v1
	v_add_u32_e32 v1, s5, v220
	s_movk_i32 s5, 0x2100
	v_mul_lo_u32 v1, v1, s5
	v_or_b32_e32 v219, v1, v214
	global_load_dwordx4 v[176:179], v[2:3], off
	global_load_dwordx4 v[180:183], v[2:3], off offset:32
	global_load_dwordx4 v[184:187], v[2:3], off offset:64
	global_load_dwordx4 v[188:191], v[2:3], off offset:96
	v_lshlrev_b32_e32 v1, 1, v219
	global_load_dwordx4 v[2:5], v217, s[52:53]
	global_load_dwordx4 v[192:195], v1, s[56:57]
	v_add_u32_e32 v1, 0x8000, v217
	global_load_dwordx4 v[196:199], v1, s[52:53]
	s_ashr_i32 s5, s4, 31
	v_readlane_b32 s36, v252, 41
	s_lshl_b64 s[4:5], s[4:5], 2
	v_readlane_b32 s40, v252, 45
	v_readlane_b32 s41, v252, 46
	s_add_u32 s4, s40, s4
	s_addc_u32 s5, s41, s5
	s_mov_b32 s76, 0
	s_mov_b32 s77, s76
	s_mov_b32 s78, s76
	s_mov_b32 s79, s76
	s_mov_b32 s80, s76
	s_mov_b32 s81, s76
	s_mov_b32 s82, s76
	s_mov_b32 s83, s76
	s_mov_b32 s84, s76
	s_mov_b32 s85, s76
	s_mov_b32 s86, s76
	s_mov_b32 s87, s76
	s_mov_b32 s88, s76
	s_mov_b32 s89, s76
	s_mov_b32 s90, s76
	s_mov_b32 s91, s76
	v_mov_b64_e32 v[64:65], s[76:77]
	v_mov_b64_e32 v[78:79], s[90:91]
	v_mov_b64_e32 v[66:67], s[78:79]
	v_mov_b64_e32 v[68:69], s[80:81]
	v_mov_b64_e32 v[70:71], s[82:83]
	v_mov_b64_e32 v[72:73], s[84:85]
	v_mov_b64_e32 v[74:75], s[86:87]
	v_mov_b64_e32 v[76:77], s[88:89]
	v_mov_b64_e32 v[158:159], v[78:79]
	s_add_i32 s25, s23, -1
	s_lshl_b32 s26, s24, 9
	s_add_i32 s27, s6, 0xffffff41
	s_add_i32 s28, s6, 0x9f
	v_mov_b64_e32 v[156:157], v[76:77]
	v_mov_b64_e32 v[154:155], v[74:75]
	v_mov_b64_e32 v[152:153], v[72:73]
	v_mov_b64_e32 v[150:151], v[70:71]
	v_mov_b64_e32 v[148:149], v[68:69]
	v_mov_b64_e32 v[146:147], v[66:67]
	v_mov_b64_e32 v[144:145], v[64:65]
	s_mov_b32 s29, s76
	v_readlane_b32 s17, v252, 8
	s_mov_b32 s94, 0xffff
	s_movk_i32 s95, 0x1a0
	s_movk_i32 s55, 0xc00
	s_movk_i32 s36, 0x101
	v_readlane_b32 s37, v252, 42
	v_readlane_b32 s38, v252, 43
	v_readlane_b32 s39, v252, 44
	v_readlane_b32 s42, v252, 47
	v_readlane_b32 s43, v252, 48
	v_readlane_b32 s44, v252, 49
	v_readlane_b32 s45, v252, 50
	v_readlane_b32 s46, v252, 51
	v_readlane_b32 s47, v252, 52
	v_readlane_b32 s48, v252, 53
	v_readlane_b32 s49, v252, 54
	v_readlane_b32 s50, v252, 55
	s_waitcnt vmcnt(0)
	ds_write_b128 v221, v[2:5]
	ds_write_b128 v241, v[192:195] offset:13312
	v_readlane_b32 s51, v252, 56
	ds_write_b128 v221, v[196:199] offset:22528
	s_waitcnt lgkmcnt(0)
	s_barrier
	ds_read_b128 v[18:21], v224 offset:6656
	ds_read_b128 v[2:5], v224
	ds_read_b128 v[22:25], v224 offset:32
	s_waitcnt lgkmcnt(1)
	v_mfma_f32_32x32x16_bf16 v[2:17], v[2:5], v[176:179], 0
	v_mfma_f32_32x32x16_bf16 v[34:49], v[18:21], v[176:179], 0
	ds_read_b128 v[18:21], v224 offset:6688
	s_waitcnt lgkmcnt(1)
	v_mfma_f32_32x32x16_bf16 v[2:17], v[22:25], v[180:183], v[2:17]
	s_waitcnt lgkmcnt(0)
	v_mfma_f32_32x32x16_bf16 v[34:49], v[18:21], v[180:183], v[34:49]
	ds_read_b128 v[18:21], v224 offset:64
	ds_read_b128 v[22:25], v224 offset:6720
	s_waitcnt lgkmcnt(1)
	v_mfma_f32_32x32x16_bf16 v[2:17], v[18:21], v[184:187], v[2:17]
	s_waitcnt lgkmcnt(0)
	v_mfma_f32_32x32x16_bf16 v[34:49], v[22:25], v[184:187], v[34:49]
	ds_read_b128 v[18:21], v224 offset:96
	ds_read_b128 v[22:25], v224 offset:6752
	s_waitcnt lgkmcnt(1)
	v_mfma_f32_32x32x16_bf16 v[2:17], v[18:21], v[188:191], v[2:17]
	global_load_dword v19, v0, s[4:5]
	s_mov_b32 s4, 0x3fb8aa3b
	s_waitcnt lgkmcnt(0)
	s_barrier
	s_nop 7
	v_max_f32_e32 v1, v3, v3
	v_mfma_f32_32x32x16_bf16 v[34:49], v[22:25], v[188:191], v[34:49]
	v_max_f32_e32 v18, v2, v2
	v_max_f32_e32 v1, v18, v1
	s_waitcnt vmcnt(0)
	v_mul_f32_e32 v20, 0x3fb8aa3b, v19
	s_nop 7
	v_max3_f32 v18, v4, v5, v35
	v_max3_f32 v1, v1, v34, v36
	v_max3_f32 v1, v1, v37, v6
	v_max3_f32 v18, v18, v8, v9
	v_max3_f32 v1, v1, v7, v38
	v_max3_f32 v18, v18, v40, v41
	v_max3_f32 v1, v1, v39, v10
	v_max3_f32 v18, v18, v12, v13
	v_max3_f32 v1, v1, v11, v42
	v_max3_f32 v18, v18, v44, v45
	v_max3_f32 v1, v1, v43, v14
	v_max3_f32 v18, v18, v16, v17
	v_max3_f32 v1, v1, v15, v46
	v_max3_f32 v18, v18, v48, v49
	v_max3_f32 v1, v1, v47, v18
	v_mov_b32_e32 v18, v1
	s_nop 1
	v_permlane32_swap_b32_e32 v1, v18
	v_max3_f32 v244, v1, v18, v20
	v_fma_f32 v1, v19, s4, -v244
	v_exp_f32_e32 v1, v1
	v_xor_b32_e32 v32, 0x80000000, v244
	v_sub_f32_e32 v30, v16, v244
	v_sub_f32_e32 v16, v2, v244
	v_add_u32_e32 v2, s24, v240
	v_sub_f32_e32 v31, v17, v244
	v_sub_f32_e32 v29, v15, v244
	v_sub_f32_e32 v28, v14, v244
	v_sub_f32_e32 v27, v13, v244
	v_sub_f32_e32 v26, v12, v244
	v_sub_f32_e32 v25, v11, v244
	v_sub_f32_e32 v24, v10, v244
	v_sub_f32_e32 v23, v9, v244
	v_sub_f32_e32 v22, v8, v244
	v_sub_f32_e32 v21, v7, v244
	v_sub_f32_e32 v20, v6, v244
	v_sub_f32_e32 v19, v5, v244
	v_sub_f32_e32 v18, v4, v244
	v_sub_f32_e32 v17, v3, v244
	v_sub_f32_e32 v63, v49, v244
	v_sub_f32_e32 v62, v48, v244
	v_sub_f32_e32 v61, v47, v244
	v_sub_f32_e32 v60, v46, v244
	v_sub_f32_e32 v59, v45, v244
	v_sub_f32_e32 v58, v44, v244
	v_sub_f32_e32 v57, v43, v244
	v_sub_f32_e32 v56, v42, v244
	v_sub_f32_e32 v55, v41, v244
	v_sub_f32_e32 v54, v40, v244
	v_sub_f32_e32 v53, v39, v244
	v_sub_f32_e32 v52, v38, v244
	v_sub_f32_e32 v51, v37, v244
	v_sub_f32_e32 v50, v36, v244
	v_sub_f32_e32 v49, v35, v244
	v_sub_f32_e32 v48, v34, v244
	v_cndmask_b32_e64 v1, 0, v1, s[2:3]
	v_subrev_u32_e32 v245, s6, v2
	s_mov_b64 s[6:7], -1
	v_mov_b32_e32 v2, 0
	v_mov_b32_e32 v33, v32
	v_mov_b32_e32 v34, v32
	v_mov_b32_e32 v35, v32
	v_mov_b32_e32 v36, v32
	v_mov_b32_e32 v37, v32
	v_mov_b32_e32 v38, v32
	v_mov_b32_e32 v39, v32
	v_mov_b32_e32 v40, v32
	v_mov_b32_e32 v41, v32
	v_mov_b32_e32 v42, v32
	v_mov_b32_e32 v43, v32
	v_mov_b32_e32 v44, v32
	v_mov_b32_e32 v45, v32
	v_mov_b32_e32 v46, v32
	v_mov_b32_e32 v47, v32
